# peel version + SwiGLU GEMM: next unit's first-segment fragment ds_reads issued at K-loop exit (before the epilogue)
# baseline (speedup 1.0000x reference)
; #define PG8_STAGE(bufoff, gbase, voff) do { _Pragma("unroll") for (int _i = 0; _i < 2; ++_i) \
;         __builtin_amdgcn_global_load_lds((const unsigned*)((const char*)(gbase) + (voff)[_i]), (PG8_LAS unsigned*)(lds + (bufoff) + ldsw + _i * 8192), 16, 0, 0); } while (0)
; #define PG8_WAIT_V(n) asm volatile("s_waitcnt vmcnt(" #n ")" ::: "memory")
; #define PG8_BAR __builtin_amdgcn_s_barrier()
; template <class Epi, class Sched, bool ALIGN_EPI = false, bool SP2 = false>
; __device__ __forceinline__ void gemm_phase(PG8_LAS unsigned char* lds, const Gemm g, const Sched& S, const Epi& E) {
;     ...
;     for (int i = 0; i < 2; ++i) { int R, C; stage_rc(tid * 16 + i * 8192, R, C); const int Rb = Epi::PERM ? ((R & ~31) + perm32(R & 31)) : R;
;         voffA[i] = g.tiledA ? (unsigned)((C >> 5) * 8192 + R * 64 + (C & 31) * 2) : (unsigned)(R * K + C) * 2u; voffB[i] = (unsigned)(Rb * K + C) * 2u; }
;     const size_t kstep = (size_t)(BK * 2);
;     const size_t kstepA = g.tiledA ? (size_t)16384 : kstep;
;     const size_t hstep = (size_t)HALF * K * 2;
;     const size_t tstep = 2 * hstep;
;     const unsigned ldsw = (unsigned)wid * 1024u;
;     const int aoff = lds_byte(wr * 64 + fr, fq * 8), boff = lds_byte(wc * 32 + fr, fq * 8);
;     ...
;         PG8_STAGE(PG8_SB(1, 0), cB + kstep, voffB); PG8_STAGE(PG8_SA(1, 0), cA + kstepA, voffA); PG8_STAGE(PG8_SB(1, 1), cB + hstep + kstep, voffB);
;         PG8_WAIT_V(6); PG8_BAR;
.LBB0_403:
	s_and_b32 s34, s7, 3
	s_add_i32 m0, s45, 0x18000
	v_lshl_add_u64 v[2:3], v[2:3], 0, s[38:39]
	s_lshl_b32 s7, s5, 13
	s_lshl_b32 s10, s34, 12
	s_waitcnt vmcnt(2)
	s_barrier
	global_load_lds_dwordx4 v[2:3], off
	s_add_i32 m0, s45, 0x1a000
	s_add_u32 s8, s22, 0x4000
	v_mov_b32_e32 v135, v1
	v_lshl_add_u64 v[2:3], v[4:5], 0, s[38:39]
	s_addc_u32 s9, s23, 0
	s_add_i32 s49, s45, 0x8000
	v_mov_b32_e32 v133, v1
	global_load_lds_dwordx4 v[2:3], off
	v_lshl_add_u64 v[2:3], s[8:9], 0, v[134:135]
	s_mov_b32 m0, s49
	s_add_i32 s50, s45, 0xa000
	global_load_lds_dwordx4 v[2:3], off
	v_lshl_add_u64 v[2:3], s[8:9], 0, v[132:133]
	s_add_u32 s8, s24, 0x40080
	s_mov_b32 m0, s50
	s_addc_u32 s9, s25, 0
	global_load_lds_dwordx4 v[2:3], off
	s_add_i32 m0, s45, 0x1c000
	v_lshl_add_u64 v[2:3], s[8:9], 0, v[0:1]
	global_load_lds_dwordx4 v[2:3], off
	v_lshl_add_u64 v[2:3], s[8:9], 0, v[130:131]
	s_add_i32 m0, s45, 0x1e000
	s_cmpk_lt_u32 s6, 0x100
	global_load_lds_dwordx4 v[2:3], off
	v_and_b32_e32 v3, 15, v6
	v_and_b32_e32 v2, 48, v6
	v_lshlrev_b32_e32 v6, 2, v3
	v_lshl_or_b32 v4, v3, 6, v2
	v_and_b32_e32 v5, 32, v6
	v_lshlrev_b32_e32 v3, 5, v3
	v_bitop3_b32 v15, v4, s7, v5 bitop3:0xde
	v_bitop3_b32 v142, v4, s10, v5 bitop3:0xde
	v_lshl_or_b32 v4, s5, 11, v3
	v_ashrrev_i32_e32 v5, 31, v4
	v_lshl_add_u64 v[4:5], v[4:5], 1, s[56:57]
	v_mov_b32_e32 v3, v1
	s_sext_i32_i16 s21, s4
	s_cselect_b64 s[6:7], -1, 0
	s_lshl_b32 s4, s5, 8
	v_lshl_add_u64 v[136:137], v[4:5], 0, v[2:3]
	v_lshlrev_b32_e32 v2, 9, v7
	s_add_i32 s4, s4, 0
	v_and_b32_e32 v2, 0xfffffc00, v2
	s_add_i32 s4, s4, 0x20000
	v_add_u32_e32 v2, v9, v2
	v_add_u32_e32 v143, s4, v6
	v_add3_u32 v2, v2, v8, v10
	s_mov_b64 s[4:5], 0x44000
	v_lshl_add_u64 v[138:139], v[2:3], 0, s[4:5]
	v_lshlrev_b32_e32 v2, 9, v11
	v_and_b32_e32 v2, 0xfffffc00, v2
	s_waitcnt vmcnt(6)
	v_add_u32_e32 v2, v13, v2
	v_add3_u32 v2, v2, v12, v14
	v_lshl_add_u64 v[140:141], v[2:3], 0, s[4:5]
	s_mov_b32 s52, 0
	v_add_u32_e32 v144, 0, v15
	s_barrier
	v_add_u32_e32 v145, s76, v142
	s_add_i32 s58, 0, 0x14000
	ds_read_b128 v[146:149], v145
	ds_read_b128 v[150:153], v145 offset:1024
	ds_read_b128 v[160:163], v145 offset:2048
	ds_read_b128 v[164:167], v145 offset:3072
	v_add_u32_e32 v145, s58, v142
	ds_read_b128 v[168:171], v145
	ds_read_b128 v[172:175], v145 offset:1024
	ds_read_b128 v[176:179], v145 offset:2048
	ds_read_b128 v[180:183], v145 offset:3072
	ds_read_b128 v[184:187], v144
	ds_read_b128 v[188:191], v144 offset:1024
	ds_read_b128 v[206:209], v144 offset:2048
	ds_read_b128 v[210:213], v144 offset:3072
	ds_read_b128 v[214:217], v144 offset:4096
	ds_read_b128 v[218:221], v144 offset:5120
	ds_read_b128 v[222:225], v144 offset:6144
	ds_read_b128 v[226:229], v144 offset:7168
	s_branch .LBB0_406

; #define PG8_STAGE(bufoff, gbase, voff) do { _Pragma("unroll") for (int _i = 0; _i < 2; ++_i) \
;         __builtin_amdgcn_global_load_lds((const unsigned*)((const char*)(gbase) + (voff)[_i]), (PG8_LAS unsigned*)(lds + (bufoff) + ldsw + _i * 8192), 16, 0, 0); } while (0)
; #define PG8_LDA(dst, b, h) do { _Pragma("unroll") for (int m = 0; m < 4; ++m) _Pragma("unroll") for (int k = 0; k < 2; ++k) dst[m][k] = *(const PG8_LAS bf16x8*)(lds + PG8_SA(b, h) + aoff + m * 2048 + k * 1024); } while (0)
; #define PG8_LDB(dst, b, h) do { _Pragma("unroll") for (int n = 0; n < 2; ++n) _Pragma("unroll") for (int k = 0; k < 2; ++k) dst[n][k] = *(const PG8_LAS bf16x8*)(lds + PG8_SB(b, h) + boff + n * 2048 + k * 1024); } while (0)
; #define PG8_WAIT_V(n) asm volatile("s_waitcnt vmcnt(" #n ")" ::: "memory")
; #define PG8_WAIT_L(n) asm volatile("s_waitcnt lgkmcnt(" #n ")" ::: "memory")
; #define PG8_BAR __builtin_amdgcn_s_barrier()
; #define PG8_SCHED __builtin_amdgcn_sched_barrier(0)
; template <class Epi, class Sched, bool ALIGN_EPI = false, bool SP2 = false>
; __device__ __forceinline__ void gemm_phase(PG8_LAS unsigned char* lds, const Gemm g, const Sched& S, const Epi& E) {
;     ...
;         const bool has_next = S.next(ui + 1, nxt);
;         const char* nA = has_next ? (const char*)g.A + (size_t)nxt.pm * tstep : cA; const char* nB = has_next ? (const char*)g.Bt + (size_t)nxt.pn * tstep : cB;
;         for (int t = 0; t < nt; t += 2) {
;             const bool last = (t == nt - 2);
;             const char* a1 = cA + (size_t)(t + 1) * kstepA;
;             const char* a2 = last ? nA : cA + (size_t)(t + 2) * kstepA; const char* b2 = last ? nB : cB + (size_t)(t + 2) * kstep;
;             const char* a3 = a2 + kstepA; const char* b3 = b2 + kstep;
;             if (last && has_next) S.a_ready(nxt);
;             if constexpr (SP2) {
;             PG8_LDB(B0, 0, 0); PG8_LDB(B1, 0, 1); PG8_SCHED; PG8_LDA(At, 0, 0); PG8_STAGE(PG8_SA(1, 1), a1 + hstep, voffA);
;             PG8_WAIT_V(8); PG8_WAIT_L(0); PG8_BAR; PG8_MMA(0, 0, At, B0); PG8_MMA(0, 1, At, B1); PG8_BAR; PG8_SCHED;
;             PG8_LDA(At, 0, 1); PG8_STAGE(PG8_SB(0, 0), b2, voffB); PG8_STAGE(PG8_SB(0, 1), b2 + hstep, voffB); PG8_STAGE(PG8_SA(0, 0), a2, voffA);
;             PG8_WAIT_V(8); PG8_WAIT_L(0); PG8_BAR; PG8_MMA(1, 0, At, B0); PG8_MMA(1, 1, At, B1); PG8_BAR; PG8_SCHED;
.LBB0_408:
	s_ashr_i32 s11, s10, 31
	s_lshl_b64 s[12:13], s[10:11], 19
	s_add_u32 s12, s30, s12
	s_addc_u32 s13, s31, s13
	s_and_b64 s[18:19], s[4:5], exec
	s_cselect_b32 s11, s13, s23
	s_cselect_b32 s53, s12, s22
	s_ashr_i32 s9, s8, 31
	s_lshl_b64 s[18:19], s[8:9], 19
	s_add_u32 s18, s37, s18
	s_addc_u32 s19, s44, s19
	s_and_b64 s[26:27], s[4:5], exec
	s_cselect_b32 s9, s19, s25
	s_cselect_b32 s54, s18, s24
	s_add_u32 s55, s24, 0x100
	s_addc_u32 s56, s25, 0
	s_mov_b32 s57, -2
	s_add_u32 s24, s22, 0x8000
	s_addc_u32 s25, s23, 0
	s_cmp_eq_u32 s57, 12
	s_cselect_b32 s42, s53, s24
	s_cselect_b32 s43, s11, s25
	s_cselect_b32 s40, s54, s55
	s_cselect_b32 s41, s9, s56
	s_add_u32 s26, s42, 0x4000
	s_addc_u32 s27, s43, 0
	s_add_i32 s58, 0, 0x14000
	v_lshl_add_u64 v[230:231], s[22:23], 0, v[140:141]
	s_add_i32 m0, s45, 0xc000
	global_load_lds_dwordx4 v[230:231], off
	v_lshl_add_u64 v[230:231], s[22:23], 0, v[138:139]
	s_add_i32 m0, s45, 0xe000
	s_nop 0
	global_load_lds_dwordx4 v[230:231], off
	s_waitcnt vmcnt(8)
	s_waitcnt lgkmcnt(0)
	s_barrier
	v_mfma_f32_16x16x32_bf16 v[126:129], v[146:149], v[184:187], 0
	v_mfma_f32_16x16x32_bf16 v[126:129], v[150:153], v[188:191], v[126:129]
	v_mfma_f32_16x16x32_bf16 v[118:121], v[164:167], v[188:191], 0
	v_mfma_f32_16x16x32_bf16 v[118:121], v[160:163], v[184:187], v[118:121]
	v_mfma_f32_16x16x32_bf16 v[102:105], v[160:163], v[206:209], 0
	v_mfma_f32_16x16x32_bf16 v[102:105], v[164:167], v[210:213], v[102:105]
	v_mfma_f32_16x16x32_bf16 v[110:113], v[150:153], v[210:213], 0
	v_mfma_f32_16x16x32_bf16 v[110:113], v[146:149], v[206:209], v[110:113]
	v_mfma_f32_16x16x32_bf16 v[94:97], v[146:149], v[214:217], 0
	v_mfma_f32_16x16x32_bf16 v[94:97], v[150:153], v[218:221], v[94:97]
	v_mfma_f32_16x16x32_bf16 v[86:89], v[164:167], v[218:221], 0
	v_mfma_f32_16x16x32_bf16 v[86:89], v[160:163], v[214:217], v[86:89]
	v_mfma_f32_16x16x32_bf16 v[70:73], v[160:163], v[222:225], 0
	v_mfma_f32_16x16x32_bf16 v[70:73], v[164:167], v[226:229], v[70:73]
	v_mfma_f32_16x16x32_bf16 v[78:81], v[150:153], v[226:229], 0
	v_mfma_f32_16x16x32_bf16 v[78:81], v[146:149], v[222:225], v[78:81]
	v_mfma_f32_16x16x32_bf16 v[122:125], v[168:171], v[184:187], 0
	v_mfma_f32_16x16x32_bf16 v[122:125], v[172:175], v[188:191], v[122:125]
	v_mfma_f32_16x16x32_bf16 v[114:117], v[180:183], v[188:191], 0
	v_mfma_f32_16x16x32_bf16 v[114:117], v[176:179], v[184:187], v[114:117]
	v_mfma_f32_16x16x32_bf16 v[98:101], v[176:179], v[206:209], 0
	v_mfma_f32_16x16x32_bf16 v[98:101], v[180:183], v[210:213], v[98:101]
	v_mfma_f32_16x16x32_bf16 v[106:109], v[172:175], v[210:213], 0
	v_mfma_f32_16x16x32_bf16 v[106:109], v[168:171], v[206:209], v[106:109]
	v_mfma_f32_16x16x32_bf16 v[90:93], v[168:171], v[214:217], 0
	v_mfma_f32_16x16x32_bf16 v[90:93], v[172:175], v[218:221], v[90:93]
	v_mfma_f32_16x16x32_bf16 v[82:85], v[180:183], v[218:221], 0
	v_mfma_f32_16x16x32_bf16 v[82:85], v[176:179], v[214:217], v[82:85]
	v_mfma_f32_16x16x32_bf16 v[66:69], v[176:179], v[222:225], 0
	v_mfma_f32_16x16x32_bf16 v[66:69], v[180:183], v[226:229], v[66:69]
	v_mfma_f32_16x16x32_bf16 v[74:77], v[172:175], v[226:229], 0
	v_mfma_f32_16x16x32_bf16 v[74:77], v[168:171], v[222:225], v[74:77]
	s_barrier
	s_add_i32 s22, s76, s29
	v_lshl_add_u64 v[230:231], s[40:41], 0, v[0:1]
	s_mov_b32 m0, s22
	ds_read_b128 v[184:187], v144 offset:16384
	ds_read_b128 v[188:191], v144 offset:17408
	ds_read_b128 v[206:209], v144 offset:18432
	ds_read_b128 v[210:213], v144 offset:19456
	ds_read_b128 v[214:217], v144 offset:20480
	ds_read_b128 v[218:221], v144 offset:21504
	ds_read_b128 v[222:225], v144 offset:22528
	ds_read_b128 v[226:229], v144 offset:23552
	global_load_lds_dwordx4 v[230:231], off
	s_add_i32 m0, s22, 0x2000
	s_add_u32 s22, s40, 0x40000
	v_lshl_add_u64 v[232:233], s[40:41], 0, v[130:131]
	s_addc_u32 s23, s41, 0
	s_add_i32 s58, s58, s29
	global_load_lds_dwordx4 v[232:233], off
	v_lshl_add_u64 v[234:235], s[22:23], 0, v[0:1]
	s_mov_b32 m0, s58
	s_nop 0
	global_load_lds_dwordx4 v[234:235], off
	v_lshl_add_u64 v[234:235], s[22:23], 0, v[130:131]
	s_add_i32 m0, s58, 0x2000
	s_nop 0
	global_load_lds_dwordx4 v[234:235], off
	v_lshl_add_u64 v[234:235], s[42:43], 0, v[134:135]
	s_mov_b32 m0, s45
	s_nop 0
	global_load_lds_dwordx4 v[234:235], off
	v_lshl_add_u64 v[234:235], s[42:43], 0, v[132:133]
	s_mov_b32 m0, s46
	s_nop 0
	global_load_lds_dwordx4 v[234:235], off
	s_waitcnt vmcnt(8)
	s_waitcnt lgkmcnt(0)
	s_barrier
	v_mfma_f32_16x16x32_bf16 v[62:65], v[146:149], v[184:187], 0
	v_mfma_f32_16x16x32_bf16 v[62:65], v[150:153], v[188:191], v[62:65]
	v_mfma_f32_16x16x32_bf16 v[54:57], v[164:167], v[188:191], 0
	v_mfma_f32_16x16x32_bf16 v[54:57], v[160:163], v[184:187], v[54:57]
	v_mfma_f32_16x16x32_bf16 v[38:41], v[160:163], v[206:209], 0
	v_mfma_f32_16x16x32_bf16 v[38:41], v[164:167], v[210:213], v[38:41]
	v_mfma_f32_16x16x32_bf16 v[46:49], v[150:153], v[210:213], 0
	v_mfma_f32_16x16x32_bf16 v[46:49], v[146:149], v[206:209], v[46:49]
	v_mfma_f32_16x16x32_bf16 v[30:33], v[146:149], v[214:217], 0
	v_mfma_f32_16x16x32_bf16 v[30:33], v[150:153], v[218:221], v[30:33]
	v_mfma_f32_16x16x32_bf16 v[22:25], v[164:167], v[218:221], 0
	v_mfma_f32_16x16x32_bf16 v[22:25], v[160:163], v[214:217], v[22:25]
	v_mfma_f32_16x16x32_bf16 v[6:9], v[160:163], v[222:225], 0
	v_mfma_f32_16x16x32_bf16 v[6:9], v[164:167], v[226:229], v[6:9]
	v_mfma_f32_16x16x32_bf16 v[14:17], v[150:153], v[226:229], 0
	v_mfma_f32_16x16x32_bf16 v[14:17], v[146:149], v[222:225], v[14:17]
	v_mfma_f32_16x16x32_bf16 v[58:61], v[168:171], v[184:187], 0
	v_mfma_f32_16x16x32_bf16 v[58:61], v[172:175], v[188:191], v[58:61]
	v_mfma_f32_16x16x32_bf16 v[50:53], v[180:183], v[188:191], 0
	v_mfma_f32_16x16x32_bf16 v[50:53], v[176:179], v[184:187], v[50:53]
	v_mfma_f32_16x16x32_bf16 v[34:37], v[176:179], v[206:209], 0
	v_mfma_f32_16x16x32_bf16 v[34:37], v[180:183], v[210:213], v[34:37]
	v_mfma_f32_16x16x32_bf16 v[42:45], v[172:175], v[210:213], 0
	v_mfma_f32_16x16x32_bf16 v[42:45], v[168:171], v[206:209], v[42:45]
	v_mfma_f32_16x16x32_bf16 v[26:29], v[168:171], v[214:217], 0
	v_mfma_f32_16x16x32_bf16 v[26:29], v[172:175], v[218:221], v[26:29]
	v_mfma_f32_16x16x32_bf16 v[18:21], v[180:183], v[218:221], 0
	v_mfma_f32_16x16x32_bf16 v[18:21], v[176:179], v[214:217], v[18:21]
	v_mfma_f32_16x16x32_bf16 v[2:5], v[176:179], v[222:225], 0
	v_mfma_f32_16x16x32_bf16 v[2:5], v[180:183], v[226:229], v[2:5]
	v_mfma_f32_16x16x32_bf16 v[10:13], v[172:175], v[226:229], 0
	v_mfma_f32_16x16x32_bf16 v[10:13], v[168:171], v[222:225], v[10:13]
	s_barrier
; #define PG8_STAGE(bufoff, gbase, voff) do { _Pragma("unroll") for (int _i = 0; _i < 2; ++_i) \
;         __builtin_amdgcn_global_load_lds((const unsigned*)((const char*)(gbase) + (voff)[_i]), (PG8_LAS unsigned*)(lds + (bufoff) + ldsw + _i * 8192), 16, 0, 0); } while (0)
; #define PG8_LDA(dst, b, h) do { _Pragma("unroll") for (int m = 0; m < 4; ++m) _Pragma("unroll") for (int k = 0; k < 2; ++k) dst[m][k] = *(const PG8_LAS bf16x8*)(lds + PG8_SA(b, h) + aoff + m * 2048 + k * 1024); } while (0)
; #define PG8_LDB(dst, b, h) do { _Pragma("unroll") for (int n = 0; n < 2; ++n) _Pragma("unroll") for (int k = 0; k < 2; ++k) dst[n][k] = *(const PG8_LAS bf16x8*)(lds + PG8_SB(b, h) + boff + n * 2048 + k * 1024); } while (0)
; template <class Epi, class Sched, bool ALIGN_EPI = false, bool SP2 = false>
; __device__ __forceinline__ void gemm_phase(PG8_LAS unsigned char* lds, const Gemm g, const Sched& S, const Epi& E) {
;     ...
;         for (int t = 0; t < nt; t += 2) {
;             const bool last = (t == nt - 2);
;             const char* a1 = cA + (size_t)(t + 1) * kstepA;
;             const char* a2 = last ? nA : cA + (size_t)(t + 2) * kstepA; const char* b2 = last ? nB : cB + (size_t)(t + 2) * kstep;
;             const char* a3 = a2 + kstepA; const char* b3 = b2 + kstep;
;             if (last && has_next) S.a_ready(nxt);
;             if constexpr (SP2) {
;             PG8_LDB(B0, 0, 0); PG8_LDB(B1, 0, 1); PG8_SCHED; PG8_LDA(At, 0, 0); PG8_STAGE(PG8_SA(1, 1), a1 + hstep, voffA);
;             PG8_WAIT_V(8); PG8_WAIT_L(0); PG8_BAR; PG8_MMA(0, 0, At, B0); PG8_MMA(0, 1, At, B1); PG8_BAR; PG8_SCHED;
;             PG8_LDA(At, 0, 1); PG8_STAGE(PG8_SB(0, 0), b2, voffB); PG8_STAGE(PG8_SB(0, 1), b2 + hstep, voffB); PG8_STAGE(PG8_SA(0, 0), a2, voffA);
;             PG8_WAIT_V(8); PG8_WAIT_L(0); PG8_BAR; PG8_MMA(1, 0, At, B0); PG8_MMA(1, 1, At, B1); PG8_BAR; PG8_SCHED;
;             PG8_LDB(B0, 1, 0); PG8_LDB(B1, 1, 1); PG8_SCHED; PG8_LDA(At, 1, 0); PG8_STAGE(PG8_SA(0, 1), a2 + hstep, voffA);
;             PG8_WAIT_V(8); PG8_WAIT_L(0); PG8_BAR; PG8_MMA(0, 0, At, B0); PG8_MMA(0, 1, At, B1); PG8_BAR; PG8_SCHED;
;             PG8_LDA(At, 1, 1); PG8_STAGE(PG8_SB(1, 0), b3, voffB); PG8_STAGE(PG8_SB(1, 1), b3 + hstep, voffB); PG8_STAGE(PG8_SA(1, 0), a3, voffA);
;             PG8_WAIT_V(8); PG8_WAIT_L(0); PG8_BAR; PG8_MMA(1, 0, At, B0); PG8_MMA(1, 1, At, B1); PG8_BAR; PG8_SCHED;
	s_add_i32 s58, 0, 0x18000
	v_add_u32_e32 v145, s58, v142
	s_add_i32 s59, 0, 0x1c000
	ds_read_b128 v[146:149], v145
	ds_read_b128 v[150:153], v145 offset:1024
	ds_read_b128 v[160:163], v145 offset:2048
	ds_read_b128 v[164:167], v145 offset:3072
	v_add_u32_e32 v145, s59, v142
	ds_read_b128 v[168:171], v145
	ds_read_b128 v[172:175], v145 offset:1024
	ds_read_b128 v[176:179], v145 offset:2048
	ds_read_b128 v[180:183], v145 offset:3072
	s_add_u32 s22, s42, 0x40000
	s_addc_u32 s23, s43, 0
	s_mov_b32 m0, s47
	v_lshl_add_u64 v[234:235], s[22:23], 0, v[134:135]
	ds_read_b128 v[184:187], v144 offset:32768
	ds_read_b128 v[188:191], v144 offset:33792
	ds_read_b128 v[206:209], v144 offset:34816
	ds_read_b128 v[210:213], v144 offset:35840
	ds_read_b128 v[214:217], v144 offset:36864
	ds_read_b128 v[218:221], v144 offset:37888
	ds_read_b128 v[222:225], v144 offset:38912
	ds_read_b128 v[226:229], v144 offset:39936
	global_load_lds_dwordx4 v[234:235], off
	v_lshl_add_u64 v[234:235], s[22:23], 0, v[132:133]
	s_mov_b32 m0, s48
	s_nop 0
	global_load_lds_dwordx4 v[234:235], off
	s_waitcnt vmcnt(8)
	s_waitcnt lgkmcnt(0)
	s_barrier
	v_mfma_f32_16x16x32_bf16 v[126:129], v[146:149], v[184:187], v[126:129]
	v_mfma_f32_16x16x32_bf16 v[126:129], v[150:153], v[188:191], v[126:129]
	v_mfma_f32_16x16x32_bf16 v[118:121], v[164:167], v[188:191], v[118:121]
	v_mfma_f32_16x16x32_bf16 v[118:121], v[160:163], v[184:187], v[118:121]
	v_mfma_f32_16x16x32_bf16 v[102:105], v[160:163], v[206:209], v[102:105]
	v_mfma_f32_16x16x32_bf16 v[102:105], v[164:167], v[210:213], v[102:105]
	v_mfma_f32_16x16x32_bf16 v[110:113], v[150:153], v[210:213], v[110:113]
	v_mfma_f32_16x16x32_bf16 v[110:113], v[146:149], v[206:209], v[110:113]
	v_mfma_f32_16x16x32_bf16 v[94:97], v[146:149], v[214:217], v[94:97]
	v_mfma_f32_16x16x32_bf16 v[94:97], v[150:153], v[218:221], v[94:97]
	v_mfma_f32_16x16x32_bf16 v[86:89], v[164:167], v[218:221], v[86:89]
	v_mfma_f32_16x16x32_bf16 v[86:89], v[160:163], v[214:217], v[86:89]
	v_mfma_f32_16x16x32_bf16 v[70:73], v[160:163], v[222:225], v[70:73]
	v_mfma_f32_16x16x32_bf16 v[70:73], v[164:167], v[226:229], v[70:73]
	v_mfma_f32_16x16x32_bf16 v[78:81], v[150:153], v[226:229], v[78:81]
	v_mfma_f32_16x16x32_bf16 v[78:81], v[146:149], v[222:225], v[78:81]
	v_mfma_f32_16x16x32_bf16 v[122:125], v[168:171], v[184:187], v[122:125]
	v_mfma_f32_16x16x32_bf16 v[122:125], v[172:175], v[188:191], v[122:125]
	v_mfma_f32_16x16x32_bf16 v[114:117], v[180:183], v[188:191], v[114:117]
	v_mfma_f32_16x16x32_bf16 v[114:117], v[176:179], v[184:187], v[114:117]
	v_mfma_f32_16x16x32_bf16 v[98:101], v[176:179], v[206:209], v[98:101]
	v_mfma_f32_16x16x32_bf16 v[98:101], v[180:183], v[210:213], v[98:101]
	v_mfma_f32_16x16x32_bf16 v[106:109], v[172:175], v[210:213], v[106:109]
	v_mfma_f32_16x16x32_bf16 v[106:109], v[168:171], v[206:209], v[106:109]
	v_mfma_f32_16x16x32_bf16 v[90:93], v[168:171], v[214:217], v[90:93]
	v_mfma_f32_16x16x32_bf16 v[90:93], v[172:175], v[218:221], v[90:93]
	v_mfma_f32_16x16x32_bf16 v[82:85], v[180:183], v[218:221], v[82:85]
	v_mfma_f32_16x16x32_bf16 v[82:85], v[176:179], v[214:217], v[82:85]
	v_mfma_f32_16x16x32_bf16 v[66:69], v[176:179], v[222:225], v[66:69]
	v_mfma_f32_16x16x32_bf16 v[66:69], v[180:183], v[226:229], v[66:69]
	v_mfma_f32_16x16x32_bf16 v[74:77], v[172:175], v[226:229], v[74:77]
	v_mfma_f32_16x16x32_bf16 v[74:77], v[168:171], v[222:225], v[74:77]
	s_barrier
	s_add_i32 s22, s58, s29
	v_lshl_add_u64 v[230:231], v[230:231], 0, s[38:39]
	s_mov_b32 m0, s22
	ds_read_b128 v[184:187], v144 offset:49152
	ds_read_b128 v[188:191], v144 offset:50176
	ds_read_b128 v[206:209], v144 offset:51200
	ds_read_b128 v[210:213], v144 offset:52224
	ds_read_b128 v[214:217], v144 offset:53248
	ds_read_b128 v[218:221], v144 offset:54272
	ds_read_b128 v[222:225], v144 offset:55296
	ds_read_b128 v[226:229], v144 offset:56320
	global_load_lds_dwordx4 v[230:231], off
	s_add_i32 m0, s22, 0x2000
	s_add_u32 s22, s40, 0x40080
	v_lshl_add_u64 v[230:231], v[232:233], 0, s[38:39]
	s_addc_u32 s23, s41, 0
	s_add_i32 s40, s59, s29
	global_load_lds_dwordx4 v[230:231], off
	v_lshl_add_u64 v[230:231], s[22:23], 0, v[0:1]
	s_mov_b32 m0, s40
	s_nop 0
	global_load_lds_dwordx4 v[230:231], off
	v_lshl_add_u64 v[230:231], s[22:23], 0, v[130:131]
	s_add_i32 m0, s40, 0x2000
	s_nop 0
	global_load_lds_dwordx4 v[230:231], off
	v_lshl_add_u64 v[230:231], s[26:27], 0, v[134:135]
	s_mov_b32 m0, s49
	s_nop 0
	global_load_lds_dwordx4 v[230:231], off
	v_lshl_add_u64 v[230:231], s[26:27], 0, v[132:133]
	s_mov_b32 m0, s50
	s_nop 0
	global_load_lds_dwordx4 v[230:231], off
	s_waitcnt vmcnt(8)
	s_waitcnt lgkmcnt(0)
	s_barrier
	v_mfma_f32_16x16x32_bf16 v[62:65], v[146:149], v[184:187], v[62:65]
	v_mfma_f32_16x16x32_bf16 v[62:65], v[150:153], v[188:191], v[62:65]
	v_mfma_f32_16x16x32_bf16 v[54:57], v[164:167], v[188:191], v[54:57]
	v_mfma_f32_16x16x32_bf16 v[54:57], v[160:163], v[184:187], v[54:57]
	v_mfma_f32_16x16x32_bf16 v[38:41], v[160:163], v[206:209], v[38:41]
	v_mfma_f32_16x16x32_bf16 v[38:41], v[164:167], v[210:213], v[38:41]
	v_mfma_f32_16x16x32_bf16 v[46:49], v[150:153], v[210:213], v[46:49]
	v_mfma_f32_16x16x32_bf16 v[46:49], v[146:149], v[206:209], v[46:49]
	v_mfma_f32_16x16x32_bf16 v[30:33], v[146:149], v[214:217], v[30:33]
	v_mfma_f32_16x16x32_bf16 v[30:33], v[150:153], v[218:221], v[30:33]
	v_mfma_f32_16x16x32_bf16 v[22:25], v[164:167], v[218:221], v[22:25]
	v_mfma_f32_16x16x32_bf16 v[22:25], v[160:163], v[214:217], v[22:25]
	v_mfma_f32_16x16x32_bf16 v[6:9], v[160:163], v[222:225], v[6:9]
	v_mfma_f32_16x16x32_bf16 v[6:9], v[164:167], v[226:229], v[6:9]
	v_mfma_f32_16x16x32_bf16 v[14:17], v[150:153], v[226:229], v[14:17]
	v_mfma_f32_16x16x32_bf16 v[14:17], v[146:149], v[222:225], v[14:17]
	v_mfma_f32_16x16x32_bf16 v[58:61], v[168:171], v[184:187], v[58:61]
	v_mfma_f32_16x16x32_bf16 v[58:61], v[172:175], v[188:191], v[58:61]
	v_mfma_f32_16x16x32_bf16 v[50:53], v[180:183], v[188:191], v[50:53]
	v_mfma_f32_16x16x32_bf16 v[50:53], v[176:179], v[184:187], v[50:53]
	v_mfma_f32_16x16x32_bf16 v[34:37], v[176:179], v[206:209], v[34:37]
	v_mfma_f32_16x16x32_bf16 v[34:37], v[180:183], v[210:213], v[34:37]
	v_mfma_f32_16x16x32_bf16 v[42:45], v[172:175], v[210:213], v[42:45]
	v_mfma_f32_16x16x32_bf16 v[42:45], v[168:171], v[206:209], v[42:45]
	v_mfma_f32_16x16x32_bf16 v[26:29], v[168:171], v[214:217], v[26:29]
	v_mfma_f32_16x16x32_bf16 v[26:29], v[172:175], v[218:221], v[26:29]
	v_mfma_f32_16x16x32_bf16 v[18:21], v[180:183], v[218:221], v[18:21]
	v_mfma_f32_16x16x32_bf16 v[18:21], v[176:179], v[214:217], v[18:21]
	v_mfma_f32_16x16x32_bf16 v[2:5], v[176:179], v[222:225], v[2:5]
	v_mfma_f32_16x16x32_bf16 v[2:5], v[180:183], v[226:229], v[2:5]
	v_mfma_f32_16x16x32_bf16 v[10:13], v[172:175], v[226:229], v[10:13]
	v_mfma_f32_16x16x32_bf16 v[10:13], v[168:171], v[222:225], v[10:13]
	s_barrier
	s_add_i32 s57, s57, 2
	s_add_u32 s55, s55, 0x100
	s_addc_u32 s56, s56, 0
	s_cmp_gt_u32 s57, 13
	s_mov_b64 s[22:23], s[24:25]
	s_cbranch_scc1 .Lpeel_exit_2

; #define GAS __attribute__((address_space(1)))
; #define PG8_LAS __attribute__((address_space(3)))
; __device__ __forceinline__ unsigned pk_bf16(float lo, float hi) { typedef __bf16 bf2 __attribute__((ext_vector_type(2))); f32x2 v = {lo, hi}; bf2 b = __builtin_convertvector(v, bf2); return __builtin_bit_cast(unsigned, b); }
; #define PG8_SCHED __builtin_amdgcn_sched_barrier(0)
;     __device__ __forceinline__ void operator()(const f32x4 (&acc)[2][2][4][2], const Unit& u, int wr, int wc, int fr, int fq, int ui) const {
;         const int row0 = u.pm * BM + wr * 64 + fr, col0 = u.pn * HALF + wc * 32 + 8 * fq;
;         const PG8_LAS float* rp = rl + ui * 256 + wr * 64 + fr;
; #pragma unroll
;         for (int ai = 0; ai < 2; ++ai)
; #pragma unroll
;             for (int m = 0; m < 4; ++m) {
;                 bf16_t* p = H + ((size_t)(2 * u.pm + ai) * (ldh >> 5) + 4 * u.pn + wc) * 4096 + (wr * 64 + m * 16 + fr) * 32 + 8 * fq;
;                 const float rr = rp[ai * HALF + m * 16], c1 = -1.4426950408889634f * rr, c2 = rr * rr;
;                 f32x4 hv[2];
; #pragma unroll
;                 for (int n = 0; n < 2; ++n) {
;                     const f32x4 g = acc[ai][0][m][n], uu = acc[ai][1][m][n];
;                     f32x4 e = g * c1;
;                     e = (f32x4){__builtin_amdgcn_exp2f(e[0]), __builtin_amdgcn_exp2f(e[1]), __builtin_amdgcn_exp2f(e[2]), __builtin_amdgcn_exp2f(e[3])};
;                     const f32x4 d = e + 1.0f;
;                     const f32x4 r = {__builtin_amdgcn_rcpf(d[0]), __builtin_amdgcn_rcpf(d[1]), __builtin_amdgcn_rcpf(d[2]), __builtin_amdgcn_rcpf(d[3])};
;                     hv[n] = (g * uu) * (r * c2);
;                 }
;                 u32x4 w;
;                 w.x = pk_bf16(hv[0][0], hv[0][1]); w.y = pk_bf16(hv[0][2], hv[0][3]); w.z = pk_bf16(hv[1][0], hv[1][1]); w.w = pk_bf16(hv[1][2], hv[1][3]);
;                 __builtin_nontemporal_store(w, (GAS u32x4*)p);
; template <class Epi, class Sched, bool ALIGN_EPI = false, bool SP2 = false>
; __device__ __forceinline__ void gemm_phase(PG8_LAS unsigned char* lds, const Gemm g, const Sched& S, const Epi& E) {
;     ...
;             PG8_LDB(B0, 0, 0); PG8_LDB(B1, 0, 1); PG8_SCHED; PG8_LDA(At, 0, 0); PG8_STAGE(PG8_SA(1, 1), a1 + hstep, voffA);
.Lpeel_exit_2:
	v_lshl_add_u32 v244, s52, 10, v143
	ds_read2_b32 v[236:237], v244 offset1:16
	v_add_u32_e32 v145, s76, v142
	s_add_i32 s58, 0, 0x14000
	ds_read_b128 v[146:149], v145
	ds_read_b128 v[150:153], v145 offset:1024
	ds_read_b128 v[160:163], v145 offset:2048
	ds_read_b128 v[164:167], v145 offset:3072
	v_add_u32_e32 v145, s58, v142
	ds_read_b128 v[168:171], v145
	ds_read_b128 v[172:175], v145 offset:1024
	ds_read_b128 v[176:179], v145 offset:2048
	ds_read_b128 v[180:183], v145 offset:3072
	ds_read_b128 v[184:187], v144
	ds_read_b128 v[188:191], v144 offset:1024
	ds_read_b128 v[206:209], v144 offset:2048
	ds_read_b128 v[210:213], v144 offset:3072
	ds_read_b128 v[214:217], v144 offset:4096
	ds_read_b128 v[218:221], v144 offset:5120
	ds_read_b128 v[222:225], v144 offset:6144
	ds_read_b128 v[226:229], v144 offset:7168
	s_and_b64 vcc, exec, s[6:7]
	s_cbranch_vccz .LBB0_412
	s_barrier
.LBB0_412:
	v_pk_mul_f32 v[124:125], v[128:129], v[124:125]
	v_pk_mul_f32 v[122:123], v[126:127], v[122:123]
	v_pk_mul_f32 v[116:117], v[120:121], v[116:117]
	v_pk_mul_f32 v[114:115], v[118:119], v[114:115]
	s_waitcnt lgkmcnt(15)
	v_mul_f32_e32 v238, 0xbfb8aa3b, v236
	v_pk_mul_f32 v[240:241], v[128:129], v[238:239] op_sel_hi:[1,0]
	v_pk_mul_f32 v[242:243], v[126:127], v[238:239] op_sel_hi:[1,0]
	v_exp_f32_e32 v240, v240
	v_exp_f32_e32 v241, v241
	v_exp_f32_e32 v242, v242
	v_exp_f32_e32 v243, v243
	v_mul_f32_e32 v236, v236, v236
	v_pk_add_f32 v[240:241], v[240:241], 1.0 op_sel_hi:[1,0]
	s_lshl_b32 s9, s20, 1
	v_rcp_f32_e32 v240, v240
	v_rcp_f32_e32 v241, v241
	v_pk_add_f32 v[242:243], v[242:243], 1.0 op_sel_hi:[1,0]
	s_mul_i32 s11, s20, 0xb0
	v_rcp_f32_e32 v242, v242
	v_rcp_f32_e32 v243, v243
	v_pk_mul_f32 v[128:129], v[236:237], v[240:241] op_sel_hi:[0,1]
	v_pk_mul_f32 v[240:241], v[120:121], v[238:239] op_sel_hi:[1,0]
	v_pk_mul_f32 v[238:239], v[118:119], v[238:239] op_sel_hi:[1,0]
	v_exp_f32_e32 v240, v240
	v_exp_f32_e32 v238, v238
	v_exp_f32_e32 v241, v241
	v_exp_f32_e32 v239, v239
	v_pk_mul_f32 v[126:127], v[236:237], v[242:243] op_sel_hi:[0,1]
	v_pk_mul_f32 v[124:125], v[124:125], v[128:129]
	v_pk_mul_f32 v[122:123], v[122:123], v[126:127]
	v_pk_add_f32 v[126:127], v[240:241], 1.0 op_sel_hi:[1,0]
	v_pk_add_f32 v[128:129], v[238:239], 1.0 op_sel_hi:[1,0]
	v_rcp_f32_e32 v126, v126
	v_rcp_f32_e32 v128, v128
	v_rcp_f32_e32 v129, v129
	v_rcp_f32_e32 v127, v127
	s_lshl_b32 s20, s21, 2
	s_ashr_i32 s21, s20, 31
	v_pk_mul_f32 v[118:119], v[236:237], v[128:129] op_sel_hi:[0,1]
	v_pk_mul_f32 v[120:121], v[236:237], v[126:127] op_sel_hi:[0,1]
	v_pk_mul_f32 v[120:121], v[116:117], v[120:121]
	v_pk_mul_f32 v[116:117], v[114:115], v[118:119]
	s_or_b64 s[20:21], s[20:21], s[34:35]
	v_cvt_pk_bf16_f32 v116, v116, v117
	v_cvt_pk_bf16_f32 v117, v120, v121
	v_mul_f32_e32 v120, 0xbfb8aa3b, v237
	v_cvt_pk_bf16_f32 v114, v122, v123
	v_pk_mul_f32 v[122:123], v[112:113], v[120:121] op_sel_hi:[1,0]
	s_mul_hi_i32 s23, s9, 0x58
	s_add_u32 s22, s11, s20
	v_exp_f32_e32 v122, v122
	v_exp_f32_e32 v123, v123
	s_addc_u32 s23, s23, s21
	s_lshl_b64 s[22:23], s[22:23], 13
	v_lshl_add_u64 v[118:119], v[136:137], 0, s[22:23]
	v_cvt_pk_bf16_f32 v115, v124, v125
	v_pk_mul_f32 v[124:125], v[110:111], v[120:121] op_sel_hi:[1,0]
	global_store_dwordx4 v[118:119], v[114:117], off nt
	v_exp_f32_e32 v124, v124
	v_exp_f32_e32 v125, v125
	v_pk_add_f32 v[116:117], v[122:123], 1.0 op_sel_hi:[1,0]
	v_mul_f32_e32 v114, v237, v237
	v_rcp_f32_e32 v116, v116
	v_rcp_f32_e32 v117, v117
	v_pk_add_f32 v[122:123], v[124:125], 1.0 op_sel_hi:[1,0]
	v_pk_mul_f32 v[108:109], v[112:113], v[108:109]
	v_rcp_f32_e32 v122, v122
	v_rcp_f32_e32 v123, v123
	v_pk_mul_f32 v[112:113], v[114:115], v[116:117] op_sel_hi:[0,1]
	v_pk_mul_f32 v[116:117], v[104:105], v[120:121] op_sel_hi:[1,0]
	v_pk_mul_f32 v[120:121], v[102:103], v[120:121] op_sel_hi:[1,0]
	v_exp_f32_e32 v116, v116
	v_exp_f32_e32 v120, v120
	v_exp_f32_e32 v117, v117
	v_exp_f32_e32 v121, v121
	v_pk_mul_f32 v[106:107], v[110:111], v[106:107]
	v_pk_mul_f32 v[110:111], v[114:115], v[122:123] op_sel_hi:[0,1]
	v_pk_mul_f32 v[108:109], v[108:109], v[112:113]
	v_pk_mul_f32 v[106:107], v[106:107], v[110:111]
	v_pk_add_f32 v[110:111], v[116:117], 1.0 op_sel_hi:[1,0]
	v_pk_add_f32 v[112:113], v[120:121], 1.0 op_sel_hi:[1,0]
	v_rcp_f32_e32 v110, v110
	v_rcp_f32_e32 v112, v112
	v_rcp_f32_e32 v113, v113
	v_rcp_f32_e32 v111, v111
	v_pk_mul_f32 v[100:101], v[104:105], v[100:101]
	v_pk_mul_f32 v[98:99], v[102:103], v[98:99]
	v_pk_mul_f32 v[102:103], v[114:115], v[112:113] op_sel_hi:[0,1]
	v_pk_mul_f32 v[104:105], v[114:115], v[110:111] op_sel_hi:[0,1]
	v_pk_mul_f32 v[104:105], v[100:101], v[104:105]
	v_pk_mul_f32 v[100:101], v[98:99], v[102:103]
	ds_read2_b32 v[102:103], v244 offset0:32 offset1:48
	v_cvt_pk_bf16_f32 v100, v100, v101
	v_cvt_pk_bf16_f32 v101, v104, v105
	v_cvt_pk_bf16_f32 v98, v106, v107
	v_cvt_pk_bf16_f32 v99, v108, v109
	s_waitcnt lgkmcnt(0)
; #define GAS __attribute__((address_space(1)))
; __device__ __forceinline__ unsigned pk_bf16(float lo, float hi) { typedef __bf16 bf2 __attribute__((ext_vector_type(2))); f32x2 v = {lo, hi}; bf2 b = __builtin_convertvector(v, bf2); return __builtin_bit_cast(unsigned, b); }
;     __device__ __forceinline__ void operator()(const f32x4 (&acc)[2][2][4][2], const Unit& u, int wr, int wc, int fr, int fq, int ui) const {
;     ...
;         for (int ai = 0; ai < 2; ++ai)
; #pragma unroll
;             for (int m = 0; m < 4; ++m) {
;                 bf16_t* p = H + ((size_t)(2 * u.pm + ai) * (ldh >> 5) + 4 * u.pn + wc) * 4096 + (wr * 64 + m * 16 + fr) * 32 + 8 * fq;
;                 const float rr = rp[ai * HALF + m * 16], c1 = -1.4426950408889634f * rr, c2 = rr * rr;
;                 f32x4 hv[2];
; #pragma unroll
;                 for (int n = 0; n < 2; ++n) {
;                     const f32x4 g = acc[ai][0][m][n], uu = acc[ai][1][m][n];
;                     f32x4 e = g * c1;
;                     e = (f32x4){__builtin_amdgcn_exp2f(e[0]), __builtin_amdgcn_exp2f(e[1]), __builtin_amdgcn_exp2f(e[2]), __builtin_amdgcn_exp2f(e[3])};
;                     const f32x4 d = e + 1.0f;
;                     const f32x4 r = {__builtin_amdgcn_rcpf(d[0]), __builtin_amdgcn_rcpf(d[1]), __builtin_amdgcn_rcpf(d[2]), __builtin_amdgcn_rcpf(d[3])};
;                     hv[n] = (g * uu) * (r * c2);
;                 }
;                 u32x4 w;
;                 w.x = pk_bf16(hv[0][0], hv[0][1]); w.y = pk_bf16(hv[0][2], hv[0][3]); w.z = pk_bf16(hv[1][0], hv[1][1]); w.w = pk_bf16(hv[1][2], hv[1][3]);
;                 __builtin_nontemporal_store(w, (GAS u32x4*)p);
	v_mul_f32_e32 v104, 0xbfb8aa3b, v102
	v_pk_mul_f32 v[106:107], v[96:97], v[104:105] op_sel_hi:[1,0]
	v_pk_mul_f32 v[108:109], v[94:95], v[104:105] op_sel_hi:[1,0]
	v_exp_f32_e32 v106, v106
	v_exp_f32_e32 v107, v107
	v_exp_f32_e32 v108, v108
	v_exp_f32_e32 v109, v109
	global_store_dwordx4 v[118:119], v[98:101], off offset:1024 nt
	v_pk_mul_f32 v[92:93], v[96:97], v[92:93]
	v_pk_mul_f32 v[90:91], v[94:95], v[90:91]
	v_pk_add_f32 v[100:101], v[106:107], 1.0 op_sel_hi:[1,0]
	v_mul_f32_e32 v98, v102, v102
	v_rcp_f32_e32 v100, v100
	v_rcp_f32_e32 v101, v101
	v_pk_add_f32 v[106:107], v[108:109], 1.0 op_sel_hi:[1,0]
	v_pk_mul_f32 v[84:85], v[88:89], v[84:85]
	v_rcp_f32_e32 v106, v106
	v_rcp_f32_e32 v107, v107
	v_pk_mul_f32 v[96:97], v[98:99], v[100:101] op_sel_hi:[0,1]
	v_pk_mul_f32 v[100:101], v[88:89], v[104:105] op_sel_hi:[1,0]
	v_pk_mul_f32 v[104:105], v[86:87], v[104:105] op_sel_hi:[1,0]
	v_exp_f32_e32 v100, v100
	v_exp_f32_e32 v104, v104
	v_exp_f32_e32 v101, v101
	v_exp_f32_e32 v105, v105
	v_pk_mul_f32 v[94:95], v[98:99], v[106:107] op_sel_hi:[0,1]
	v_pk_mul_f32 v[92:93], v[92:93], v[96:97]
	v_pk_mul_f32 v[90:91], v[90:91], v[94:95]
	v_pk_add_f32 v[94:95], v[100:101], 1.0 op_sel_hi:[1,0]
	v_pk_add_f32 v[96:97], v[104:105], 1.0 op_sel_hi:[1,0]
	v_rcp_f32_e32 v94, v94
	v_rcp_f32_e32 v96, v96
	v_rcp_f32_e32 v97, v97
	v_rcp_f32_e32 v95, v95
	v_pk_mul_f32 v[82:83], v[86:87], v[82:83]
	v_pk_mul_f32 v[76:77], v[80:81], v[76:77]
	v_pk_mul_f32 v[86:87], v[98:99], v[96:97] op_sel_hi:[0,1]
	v_pk_mul_f32 v[88:89], v[98:99], v[94:95] op_sel_hi:[0,1]
	v_pk_mul_f32 v[88:89], v[84:85], v[88:89]
	v_pk_mul_f32 v[84:85], v[82:83], v[86:87]
	v_mul_f32_e32 v86, 0xbfb8aa3b, v103
	v_cvt_pk_bf16_f32 v84, v84, v85
	v_cvt_pk_bf16_f32 v85, v88, v89
	v_pk_mul_f32 v[88:89], v[80:81], v[86:87] op_sel_hi:[1,0]
	v_cvt_pk_bf16_f32 v82, v90, v91
	v_exp_f32_e32 v88, v88
	v_exp_f32_e32 v89, v89
	v_cvt_pk_bf16_f32 v83, v92, v93
	v_pk_mul_f32 v[90:91], v[78:79], v[86:87] op_sel_hi:[1,0]
	global_store_dwordx4 v[118:119], v[82:85], off offset:2048 nt
	v_exp_f32_e32 v90, v90
	v_exp_f32_e32 v91, v91
	v_pk_add_f32 v[84:85], v[88:89], 1.0 op_sel_hi:[1,0]
	v_mul_f32_e32 v82, v103, v103
	v_rcp_f32_e32 v84, v84
	v_rcp_f32_e32 v85, v85
	v_pk_add_f32 v[88:89], v[90:91], 1.0 op_sel_hi:[1,0]
	v_pk_mul_f32 v[74:75], v[78:79], v[74:75]
	v_rcp_f32_e32 v88, v88
	v_rcp_f32_e32 v89, v89
	v_pk_mul_f32 v[80:81], v[82:83], v[84:85] op_sel_hi:[0,1]
	v_pk_mul_f32 v[84:85], v[72:73], v[86:87] op_sel_hi:[1,0]
	v_pk_mul_f32 v[86:87], v[70:71], v[86:87] op_sel_hi:[1,0]
	v_exp_f32_e32 v84, v84
	v_exp_f32_e32 v86, v86
	v_exp_f32_e32 v85, v85
	v_exp_f32_e32 v87, v87
	v_pk_mul_f32 v[78:79], v[82:83], v[88:89] op_sel_hi:[0,1]
	v_pk_mul_f32 v[76:77], v[76:77], v[80:81]
	v_pk_mul_f32 v[74:75], v[74:75], v[78:79]
	v_pk_add_f32 v[78:79], v[84:85], 1.0 op_sel_hi:[1,0]
	v_pk_add_f32 v[80:81], v[86:87], 1.0 op_sel_hi:[1,0]
	v_rcp_f32_e32 v78, v78
	v_rcp_f32_e32 v80, v80
	v_rcp_f32_e32 v81, v81
	v_rcp_f32_e32 v79, v79
	v_pk_mul_f32 v[68:69], v[72:73], v[68:69]
	v_pk_mul_f32 v[66:67], v[70:71], v[66:67]
	v_pk_mul_f32 v[70:71], v[82:83], v[80:81] op_sel_hi:[0,1]
	v_pk_mul_f32 v[72:73], v[82:83], v[78:79] op_sel_hi:[0,1]
	v_pk_mul_f32 v[72:73], v[68:69], v[72:73]
	v_pk_mul_f32 v[68:69], v[66:67], v[70:71]
	v_cvt_pk_bf16_f32 v66, v74, v75
	v_cvt_pk_bf16_f32 v67, v76, v77
	v_cvt_pk_bf16_f32 v68, v68, v69
	v_cvt_pk_bf16_f32 v69, v72, v73
	global_store_dwordx4 v[118:119], v[66:69], off offset:3072 nt
	ds_read2_b32 v[66:67], v244 offset0:128 offset1:144
	v_pk_mul_f32 v[60:61], v[64:65], v[60:61]
	v_pk_mul_f32 v[58:59], v[62:63], v[58:59]
	v_pk_mul_f32 v[52:53], v[56:57], v[52:53]
	v_pk_mul_f32 v[50:51], v[54:55], v[50:51]
	s_waitcnt lgkmcnt(0)
; #define GAS __attribute__((address_space(1)))
; __device__ __forceinline__ unsigned pk_bf16(float lo, float hi) { typedef __bf16 bf2 __attribute__((ext_vector_type(2))); f32x2 v = {lo, hi}; bf2 b = __builtin_convertvector(v, bf2); return __builtin_bit_cast(unsigned, b); }
; #define PG8_BAR __builtin_amdgcn_s_barrier()
;     __device__ __forceinline__ void operator()(const f32x4 (&acc)[2][2][4][2], const Unit& u, int wr, int wc, int fr, int fq, int ui) const {
;     ...
;         for (int ai = 0; ai < 2; ++ai)
; #pragma unroll
;             for (int m = 0; m < 4; ++m) {
;                 bf16_t* p = H + ((size_t)(2 * u.pm + ai) * (ldh >> 5) + 4 * u.pn + wc) * 4096 + (wr * 64 + m * 16 + fr) * 32 + 8 * fq;
;                 const float rr = rp[ai * HALF + m * 16], c1 = -1.4426950408889634f * rr, c2 = rr * rr;
;                 f32x4 hv[2];
; #pragma unroll
;                 for (int n = 0; n < 2; ++n) {
;                     const f32x4 g = acc[ai][0][m][n], uu = acc[ai][1][m][n];
;                     f32x4 e = g * c1;
;                     e = (f32x4){__builtin_amdgcn_exp2f(e[0]), __builtin_amdgcn_exp2f(e[1]), __builtin_amdgcn_exp2f(e[2]), __builtin_amdgcn_exp2f(e[3])};
;                     const f32x4 d = e + 1.0f;
;                     const f32x4 r = {__builtin_amdgcn_rcpf(d[0]), __builtin_amdgcn_rcpf(d[1]), __builtin_amdgcn_rcpf(d[2]), __builtin_amdgcn_rcpf(d[3])};
;                     hv[n] = (g * uu) * (r * c2);
;                 }
;                 u32x4 w;
;                 w.x = pk_bf16(hv[0][0], hv[0][1]); w.y = pk_bf16(hv[0][2], hv[0][3]); w.z = pk_bf16(hv[1][0], hv[1][1]); w.w = pk_bf16(hv[1][2], hv[1][3]);
;                 __builtin_nontemporal_store(w, (GAS u32x4*)p);
; template <class Epi, class Sched, bool ALIGN_EPI = false, bool SP2 = false>
; __device__ __forceinline__ void gemm_phase(PG8_LAS unsigned char* lds, const Gemm g, const Sched& S, const Epi& E) {
;     ...
;         if (!has_next) break;
; #pragma unroll
;         for (int a = 0; a < 2; ++a)
; #pragma unroll
;             for (int b = 0; b < 2; ++b)
; #pragma unroll
;                 for (int m = 0; m < 4; ++m)
; #pragma unroll
;                     for (int n = 0; n < 2; ++n) acc[a][b][m][n] = (f32x4){0.f, 0.f, 0.f, 0.f};
;         cur = nxt; cA = nA; cB = nB; ++ui;
;         if constexpr (ALIGN_EPI) { if (wr == 1) PG8_BAR; }
	v_mul_f32_e32 v68, 0xbfb8aa3b, v66
	v_pk_mul_f32 v[70:71], v[64:65], v[68:69] op_sel_hi:[1,0]
	v_pk_mul_f32 v[72:73], v[62:63], v[68:69] op_sel_hi:[1,0]
	v_exp_f32_e32 v70, v70
	v_exp_f32_e32 v71, v71
	v_exp_f32_e32 v72, v72
	v_exp_f32_e32 v73, v73
	v_mul_f32_e32 v66, v66, v66
	v_pk_add_f32 v[70:71], v[70:71], 1.0 op_sel_hi:[1,0]
	s_or_b32 s9, s9, 1
	v_rcp_f32_e32 v70, v70
	v_rcp_f32_e32 v71, v71
	v_pk_add_f32 v[72:73], v[72:73], 1.0 op_sel_hi:[1,0]
	s_mul_hi_i32 s11, s9, 0x58
	v_rcp_f32_e32 v72, v72
	v_rcp_f32_e32 v73, v73
	v_pk_mul_f32 v[64:65], v[66:67], v[70:71] op_sel_hi:[0,1]
	v_pk_mul_f32 v[70:71], v[56:57], v[68:69] op_sel_hi:[1,0]
	v_pk_mul_f32 v[68:69], v[54:55], v[68:69] op_sel_hi:[1,0]
	v_exp_f32_e32 v70, v70
	v_exp_f32_e32 v68, v68
	v_exp_f32_e32 v71, v71
	v_exp_f32_e32 v69, v69
	v_pk_mul_f32 v[62:63], v[66:67], v[72:73] op_sel_hi:[0,1]
	v_pk_mul_f32 v[60:61], v[60:61], v[64:65]
	v_pk_mul_f32 v[58:59], v[58:59], v[62:63]
	v_pk_add_f32 v[62:63], v[70:71], 1.0 op_sel_hi:[1,0]
	v_pk_add_f32 v[64:65], v[68:69], 1.0 op_sel_hi:[1,0]
	v_rcp_f32_e32 v62, v62
	v_rcp_f32_e32 v64, v64
	v_rcp_f32_e32 v65, v65
	v_rcp_f32_e32 v63, v63
	s_mulk_i32 s9, 0x58
	s_add_u32 s20, s9, s20
	v_pk_mul_f32 v[54:55], v[66:67], v[64:65] op_sel_hi:[0,1]
	v_pk_mul_f32 v[56:57], v[66:67], v[62:63] op_sel_hi:[0,1]
	v_pk_mul_f32 v[56:57], v[52:53], v[56:57]
	v_pk_mul_f32 v[52:53], v[50:51], v[54:55]
	v_cvt_pk_bf16_f32 v50, v58, v59
	v_cvt_pk_bf16_f32 v52, v52, v53
	v_cvt_pk_bf16_f32 v53, v56, v57
	v_mul_f32_e32 v56, 0xbfb8aa3b, v67
	v_pk_mul_f32 v[58:59], v[48:49], v[56:57] op_sel_hi:[1,0]
	s_addc_u32 s21, s11, s21
	v_exp_f32_e32 v58, v58
	v_exp_f32_e32 v59, v59
	s_lshl_b64 s[20:21], s[20:21], 13
	v_lshl_add_u64 v[54:55], v[136:137], 0, s[20:21]
	v_cvt_pk_bf16_f32 v51, v60, v61
	v_pk_mul_f32 v[60:61], v[46:47], v[56:57] op_sel_hi:[1,0]
	global_store_dwordx4 v[54:55], v[50:53], off nt
	v_exp_f32_e32 v60, v60
	v_exp_f32_e32 v61, v61
	v_pk_add_f32 v[52:53], v[58:59], 1.0 op_sel_hi:[1,0]
	v_mul_f32_e32 v50, v67, v67
	v_rcp_f32_e32 v52, v52
	v_rcp_f32_e32 v53, v53
	v_pk_add_f32 v[58:59], v[60:61], 1.0 op_sel_hi:[1,0]
	v_pk_mul_f32 v[44:45], v[48:49], v[44:45]
	v_rcp_f32_e32 v58, v58
	v_rcp_f32_e32 v59, v59
	v_pk_mul_f32 v[48:49], v[50:51], v[52:53] op_sel_hi:[0,1]
	v_pk_mul_f32 v[52:53], v[40:41], v[56:57] op_sel_hi:[1,0]
	v_pk_mul_f32 v[56:57], v[38:39], v[56:57] op_sel_hi:[1,0]
	v_exp_f32_e32 v52, v52
	v_exp_f32_e32 v56, v56
	v_exp_f32_e32 v53, v53
	v_exp_f32_e32 v57, v57
	v_pk_mul_f32 v[42:43], v[46:47], v[42:43]
	v_pk_mul_f32 v[46:47], v[50:51], v[58:59] op_sel_hi:[0,1]
	v_pk_mul_f32 v[44:45], v[44:45], v[48:49]
	v_pk_mul_f32 v[42:43], v[42:43], v[46:47]
	v_pk_add_f32 v[46:47], v[52:53], 1.0 op_sel_hi:[1,0]
	v_pk_add_f32 v[48:49], v[56:57], 1.0 op_sel_hi:[1,0]
	v_rcp_f32_e32 v46, v46
	v_rcp_f32_e32 v48, v48
	v_rcp_f32_e32 v49, v49
	v_rcp_f32_e32 v47, v47
	v_pk_mul_f32 v[36:37], v[40:41], v[36:37]
	v_pk_mul_f32 v[34:35], v[38:39], v[34:35]
	v_pk_mul_f32 v[38:39], v[50:51], v[48:49] op_sel_hi:[0,1]
	v_pk_mul_f32 v[40:41], v[50:51], v[46:47] op_sel_hi:[0,1]
	v_pk_mul_f32 v[40:41], v[36:37], v[40:41]
	v_pk_mul_f32 v[36:37], v[34:35], v[38:39]
	ds_read2_b32 v[38:39], v244 offset0:160 offset1:176
	v_cvt_pk_bf16_f32 v36, v36, v37
	v_cvt_pk_bf16_f32 v37, v40, v41
	v_cvt_pk_bf16_f32 v34, v42, v43
	v_cvt_pk_bf16_f32 v35, v44, v45
	s_waitcnt lgkmcnt(0)
	v_mul_f32_e32 v40, 0xbfb8aa3b, v38
	v_pk_mul_f32 v[42:43], v[32:33], v[40:41] op_sel_hi:[1,0]
	v_pk_mul_f32 v[44:45], v[30:31], v[40:41] op_sel_hi:[1,0]
	v_exp_f32_e32 v42, v42
	v_exp_f32_e32 v43, v43
	v_exp_f32_e32 v44, v44
	v_exp_f32_e32 v45, v45
	global_store_dwordx4 v[54:55], v[34:37], off offset:1024 nt
	v_pk_mul_f32 v[28:29], v[32:33], v[28:29]
	v_pk_mul_f32 v[26:27], v[30:31], v[26:27]
	v_pk_add_f32 v[36:37], v[42:43], 1.0 op_sel_hi:[1,0]
	v_mul_f32_e32 v34, v38, v38
	v_rcp_f32_e32 v36, v36
	v_rcp_f32_e32 v37, v37
	v_pk_add_f32 v[42:43], v[44:45], 1.0 op_sel_hi:[1,0]
	v_pk_mul_f32 v[20:21], v[24:25], v[20:21]
	v_rcp_f32_e32 v42, v42
	v_rcp_f32_e32 v43, v43
	v_pk_mul_f32 v[32:33], v[34:35], v[36:37] op_sel_hi:[0,1]
	v_pk_mul_f32 v[36:37], v[24:25], v[40:41] op_sel_hi:[1,0]
	v_pk_mul_f32 v[40:41], v[22:23], v[40:41] op_sel_hi:[1,0]
	v_exp_f32_e32 v36, v36
	v_exp_f32_e32 v40, v40
	v_exp_f32_e32 v37, v37
	v_exp_f32_e32 v41, v41
	v_pk_mul_f32 v[30:31], v[34:35], v[42:43] op_sel_hi:[0,1]
	v_pk_mul_f32 v[28:29], v[28:29], v[32:33]
	v_pk_mul_f32 v[26:27], v[26:27], v[30:31]
	v_pk_add_f32 v[30:31], v[36:37], 1.0 op_sel_hi:[1,0]
	v_pk_add_f32 v[32:33], v[40:41], 1.0 op_sel_hi:[1,0]
	v_rcp_f32_e32 v30, v30
	v_rcp_f32_e32 v32, v32
	v_rcp_f32_e32 v33, v33
	v_rcp_f32_e32 v31, v31
	v_pk_mul_f32 v[18:19], v[22:23], v[18:19]
	v_pk_mul_f32 v[12:13], v[16:17], v[12:13]
	v_pk_mul_f32 v[22:23], v[34:35], v[32:33] op_sel_hi:[0,1]
	v_pk_mul_f32 v[24:25], v[34:35], v[30:31] op_sel_hi:[0,1]
	v_pk_mul_f32 v[24:25], v[20:21], v[24:25]
	v_pk_mul_f32 v[20:21], v[18:19], v[22:23]
	v_mul_f32_e32 v22, 0xbfb8aa3b, v39
	v_cvt_pk_bf16_f32 v20, v20, v21
	v_cvt_pk_bf16_f32 v21, v24, v25
	v_pk_mul_f32 v[24:25], v[16:17], v[22:23] op_sel_hi:[1,0]
	v_cvt_pk_bf16_f32 v18, v26, v27
	v_exp_f32_e32 v24, v24
	v_exp_f32_e32 v25, v25
	v_cvt_pk_bf16_f32 v19, v28, v29
	v_pk_mul_f32 v[26:27], v[14:15], v[22:23] op_sel_hi:[1,0]
	global_store_dwordx4 v[54:55], v[18:21], off offset:2048 nt
	v_exp_f32_e32 v26, v26
	v_exp_f32_e32 v27, v27
	v_pk_add_f32 v[20:21], v[24:25], 1.0 op_sel_hi:[1,0]
	v_mul_f32_e32 v18, v39, v39
	v_rcp_f32_e32 v20, v20
	v_rcp_f32_e32 v21, v21
	v_pk_add_f32 v[24:25], v[26:27], 1.0 op_sel_hi:[1,0]
	v_pk_mul_f32 v[10:11], v[14:15], v[10:11]
	v_rcp_f32_e32 v24, v24
	v_rcp_f32_e32 v25, v25
	v_pk_mul_f32 v[16:17], v[18:19], v[20:21] op_sel_hi:[0,1]
	v_pk_mul_f32 v[20:21], v[8:9], v[22:23] op_sel_hi:[1,0]
	v_pk_mul_f32 v[22:23], v[6:7], v[22:23] op_sel_hi:[1,0]
	v_exp_f32_e32 v20, v20
	v_exp_f32_e32 v22, v22
	v_exp_f32_e32 v21, v21
	v_exp_f32_e32 v23, v23
	v_pk_mul_f32 v[14:15], v[18:19], v[24:25] op_sel_hi:[0,1]
	v_pk_mul_f32 v[12:13], v[12:13], v[16:17]
	v_pk_mul_f32 v[10:11], v[10:11], v[14:15]
	v_pk_add_f32 v[14:15], v[20:21], 1.0 op_sel_hi:[1,0]
	v_pk_add_f32 v[16:17], v[22:23], 1.0 op_sel_hi:[1,0]
	v_rcp_f32_e32 v14, v14
	v_rcp_f32_e32 v16, v16
	v_rcp_f32_e32 v17, v17
	v_rcp_f32_e32 v15, v15
	v_pk_mul_f32 v[4:5], v[8:9], v[4:5]
	v_pk_mul_f32 v[2:3], v[6:7], v[2:3]
	v_pk_mul_f32 v[6:7], v[18:19], v[16:17] op_sel_hi:[0,1]
	v_pk_mul_f32 v[8:9], v[18:19], v[14:15] op_sel_hi:[0,1]
	v_pk_mul_f32 v[8:9], v[4:5], v[8:9]
	v_pk_mul_f32 v[4:5], v[2:3], v[6:7]
	v_cvt_pk_bf16_f32 v2, v10, v11
	v_cvt_pk_bf16_f32 v3, v12, v13
	v_cvt_pk_bf16_f32 v4, v4, v5
	v_cvt_pk_bf16_f32 v5, v8, v9
	s_andn2_b64 vcc, exec, s[4:5]
	s_mov_b64 s[4:5], -1
	s_movk_i32 s54, 0x7fff
	global_store_dwordx4 v[54:55], v[2:5], off offset:3072 nt
	s_cbranch_vccnz .LBB0_405
	s_andn2_b64 vcc, exec, s[2:3]
	s_cbranch_vccnz .LBB0_404
	s_barrier
	s_branch .LBB0_404
